# RS2: SwiGLU epilogue loads the workgroup's row scales once per phase (first unit) instead of per unit, on top of v068
# baseline (speedup 1.0000x reference)
.Lnb0_done:
	v_ashrrev_i32_e32 v199, 31, v198
	v_lshl_add_u64 v[132:133], v[198:199], 2, s[50:51]
	s_cmp_eq_u32 s46, 1
	s_cbranch_scc1 .Lrs_load
	s_cmpk_eq_u32 s98, 0x100
	s_cbranch_scc1 .Lrs_cached
.Lrs_load:
	global_load_dword v240, v[132:133], off
	global_load_dword v241, v[132:133], off offset:64
	global_load_dword v242, v[132:133], off offset:128
	global_load_dword v244, v[132:133], off offset:192
	global_load_dword v245, v[132:133], off offset:512
	global_load_dword v246, v[132:133], off offset:576
	global_load_dword v247, v[132:133], off offset:640
	global_load_dword v251, v[132:133], off offset:704
	s_waitcnt vmcnt(0)
.Lrs_cached:
	v_lshl_or_b32 v130, s88, 7, v237
	s_waitcnt lgkmcnt(0)
	v_mad_u64_u32 v[134:135], s[0:1], v198, s29, v[130:131]
	v_mov_b32_e32 v136, v240
	v_mov_b32_e32 v137, v241
	v_mov_b32_e32 v135, v242
	v_mov_b32_e32 v138, v244
	v_mov_b32_e32 v139, v245
	v_mov_b32_e32 v140, v246
	v_mov_b32_e32 v131, v247
	v_mov_b32_e32 v130, v251
	v_lshlrev_b32_e32 v133, 1, v134
	s_mul_i32 s0, s29, 0x50
	v_fmamk_f32 v132, v136, 0x3a800000, v221
	v_rsq_f32_e32 v132, v132
	v_fmamk_f32 v136, v137, 0x3a800000, v221
	v_rsq_f32_e32 v136, v136
	v_pk_mul_f32 v[126:127], v[126:127], v[132:133] op_sel_hi:[1,0]
	v_pk_mul_f32 v[114:115], v[114:115], v[132:133] op_sel_hi:[1,0]
	v_pk_mul_f32 v[128:129], v[128:129], v[132:133] op_sel_hi:[1,0]
	v_pk_mul_f32 v[116:117], v[116:117], v[132:133] op_sel_hi:[1,0]
	v_pk_mul_f32 v[122:123], v[122:123], v[132:133] op_sel_hi:[1,0]
	v_pk_mul_f32 v[110:111], v[110:111], v[132:133] op_sel_hi:[1,0]
	v_pk_mul_f32 v[124:125], v[124:125], v[132:133] op_sel_hi:[1,0]
	v_pk_mul_f32 v[112:113], v[112:113], v[132:133] op_sel_hi:[1,0]
	v_pk_mul_f32 v[118:119], v[118:119], v[136:137] op_sel_hi:[1,0]
	v_pk_mul_f32 v[106:107], v[106:107], v[136:137] op_sel_hi:[1,0]
	v_pk_mul_f32 v[120:121], v[120:121], v[136:137] op_sel_hi:[1,0]
	v_pk_mul_f32 v[108:109], v[108:109], v[136:137] op_sel_hi:[1,0]
	v_pk_mul_f32 v[102:103], v[102:103], v[136:137] op_sel_hi:[1,0]
	v_mul_f32_e32 v132, 0xbfb8aa3b, v126
	v_pk_mul_f32 v[114:115], v[126:127], v[114:115]
	v_mul_f32_e32 v126, 0xbfb8aa3b, v127
	v_mul_f32_e32 v127, 0xbfb8aa3b, v128
	v_pk_mul_f32 v[116:117], v[128:129], v[116:117]
	v_mul_f32_e32 v128, 0xbfb8aa3b, v129
	v_mul_f32_e32 v129, 0xbfb8aa3b, v122
	v_pk_mul_f32 v[110:111], v[122:123], v[110:111]
	v_mul_f32_e32 v122, 0xbfb8aa3b, v123
	v_mul_f32_e32 v123, 0xbfb8aa3b, v124
	v_pk_mul_f32 v[112:113], v[124:125], v[112:113]
	v_mul_f32_e32 v124, 0xbfb8aa3b, v125
	v_mul_f32_e32 v125, 0xbfb8aa3b, v118
	v_pk_mul_f32 v[106:107], v[118:119], v[106:107]
	v_mul_f32_e32 v118, 0xbfb8aa3b, v119
	v_mul_f32_e32 v119, 0xbfb8aa3b, v120
	v_pk_mul_f32 v[108:109], v[120:121], v[108:109]
	v_mul_f32_e32 v120, 0xbfb8aa3b, v121
	v_mul_f32_e32 v121, 0xbfb8aa3b, v102
	v_exp_f32_e32 v132, v132
	v_exp_f32_e32 v126, v126
	v_exp_f32_e32 v127, v127
	v_exp_f32_e32 v128, v128
	v_exp_f32_e32 v129, v129
	v_exp_f32_e32 v122, v122
	v_exp_f32_e32 v123, v123
	v_exp_f32_e32 v124, v124
	v_mul_f32_e32 v137, 0xbfb8aa3b, v103
	v_exp_f32_e32 v125, v125
	v_exp_f32_e32 v118, v118
	v_exp_f32_e32 v119, v119
	v_exp_f32_e32 v120, v120
	v_exp_f32_e32 v121, v121
	v_exp_f32_e32 v137, v137
	v_add_f32_e32 v132, 1.0, v132
	v_add_f32_e32 v126, 1.0, v126
	v_add_f32_e32 v127, 1.0, v127
	v_add_f32_e32 v128, 1.0, v128
	v_add_f32_e32 v129, 1.0, v129
	v_add_f32_e32 v141, 1.0, v122
	v_add_f32_e32 v142, 1.0, v123
	v_add_f32_e32 v143, 1.0, v124
	v_add_f32_e32 v144, 1.0, v125
	v_add_f32_e32 v145, 1.0, v118
	v_add_f32_e32 v146, 1.0, v119
	v_add_f32_e32 v147, 1.0, v120
	v_add_f32_e32 v148, 1.0, v121
	v_rcp_f32_e32 v118, v132
	v_rcp_f32_e32 v119, v126
	v_rcp_f32_e32 v120, v127
	v_rcp_f32_e32 v121, v128
	v_rcp_f32_e32 v122, v129
	v_rcp_f32_e32 v123, v141
	v_rcp_f32_e32 v124, v142
	v_rcp_f32_e32 v125, v143
	v_rcp_f32_e32 v126, v144
	v_rcp_f32_e32 v127, v145
	v_rcp_f32_e32 v128, v146
	v_rcp_f32_e32 v129, v147
	v_pk_mul_f32 v[98:99], v[98:99], v[136:137] op_sel_hi:[1,0]
	v_pk_mul_f32 v[114:115], v[114:115], v[118:119]
	v_pk_mul_f32 v[98:99], v[102:103], v[98:99]
	v_pk_mul_f32 v[102:103], v[104:105], v[136:137] op_sel_hi:[1,0]
	v_pk_mul_f32 v[116:117], v[116:117], v[120:121]
	v_mul_f32_e32 v104, 0xbfb8aa3b, v102
	v_mul_f32_e32 v105, 0xbfb8aa3b, v103
	v_pk_mul_f32 v[110:111], v[110:111], v[122:123]
	v_pk_mul_f32 v[112:113], v[112:113], v[124:125]
	v_exp_f32_e32 v104, v104
	v_exp_f32_e32 v105, v105
	v_pk_mul_f32 v[118:119], v[106:107], v[126:127]
	v_pk_mul_f32 v[120:121], v[108:109], v[128:129]
	v_cvt_pk_bf16_f32 v106, v114, v115
	v_cvt_pk_bf16_f32 v107, v116, v117
	v_cvt_pk_bf16_f32 v108, v110, v111
	v_cvt_pk_bf16_f32 v109, v112, v113
	buffer_store_dwordx4 v[106:109], v133, s[20:23], 0 offen sc1
	v_add_f32_e32 v104, 1.0, v104
	v_add_f32_e32 v105, 1.0, v105
	v_add_f32_e32 v107, 1.0, v137
	v_rcp_f32_e32 v106, v148
	v_rcp_f32_e32 v107, v107
	v_rcp_f32_e32 v104, v104
	v_rcp_f32_e32 v105, v105
	v_pk_mul_f32 v[106:107], v[98:99], v[106:107]
	v_pk_mul_f32 v[98:99], v[100:101], v[136:137] op_sel_hi:[1,0]
	s_nop 0
	v_pk_mul_f32 v[98:99], v[102:103], v[98:99]
	s_nop 0
	v_pk_mul_f32 v[102:103], v[98:99], v[104:105]
	v_fmamk_f32 v98, v135, 0x3a800000, v221
	v_rsq_f32_e32 v104, v98
	v_add_u32_e32 v105, s53, v134
	v_lshlrev_b32_e32 v108, 1, v105
	v_cvt_pk_bf16_f32 v98, v118, v119
	v_pk_mul_f32 v[94:95], v[94:95], v[104:105] op_sel_hi:[1,0]
	v_cvt_pk_bf16_f32 v99, v120, v121
	v_mul_f32_e32 v100, 0xbfb8aa3b, v94
	v_exp_f32_e32 v109, v100
	v_cvt_pk_bf16_f32 v100, v106, v107
	v_cvt_pk_bf16_f32 v101, v102, v103
	buffer_store_dwordx4 v[98:101], v108, s[20:23], 0 offen sc1
	v_pk_mul_f32 v[86:87], v[86:87], v[104:105] op_sel_hi:[1,0]
	v_pk_mul_f32 v[90:91], v[90:91], v[104:105] op_sel_hi:[1,0]
	v_mul_f32_e32 v99, 0xbfb8aa3b, v95
	v_exp_f32_e32 v99, v99
	v_add_f32_e32 v98, 1.0, v109
	v_pk_mul_f32 v[86:87], v[94:95], v[86:87]
	v_rcp_f32_e32 v98, v98
	v_add_f32_e32 v94, 1.0, v99
	v_rcp_f32_e32 v99, v94
	v_pk_mul_f32 v[94:95], v[96:97], v[104:105] op_sel_hi:[1,0]
	v_pk_mul_f32 v[88:89], v[88:89], v[104:105] op_sel_hi:[1,0]
	v_mul_f32_e32 v97, 0xbfb8aa3b, v95
	v_pk_mul_f32 v[86:87], v[86:87], v[98:99]
	v_mul_f32_e32 v98, 0xbfb8aa3b, v90
	v_pk_mul_f32 v[88:89], v[94:95], v[88:89]
	v_mul_f32_e32 v95, 0xbfb8aa3b, v91
	v_pk_mul_f32 v[82:83], v[82:83], v[104:105] op_sel_hi:[1,0]
	v_exp_f32_e32 v98, v98
	v_exp_f32_e32 v95, v95
	v_pk_mul_f32 v[82:83], v[90:91], v[82:83]
	v_pk_mul_f32 v[90:91], v[92:93], v[104:105] op_sel_hi:[1,0]
	v_mul_f32_e32 v96, 0xbfb8aa3b, v94
	v_mul_f32_e32 v92, 0xbfb8aa3b, v90
	v_mul_f32_e32 v93, 0xbfb8aa3b, v91
	v_exp_f32_e32 v92, v92
	v_exp_f32_e32 v93, v93
	v_add_f32_e32 v94, 1.0, v98
	v_add_f32_e32 v95, 1.0, v95
	v_rcp_f32_e32 v94, v94
	v_rcp_f32_e32 v95, v95
	v_add_f32_e32 v92, 1.0, v92
	v_add_f32_e32 v93, 1.0, v93
	v_rcp_f32_e32 v92, v92
	v_rcp_f32_e32 v93, v93
	v_exp_f32_e32 v96, v96
	v_exp_f32_e32 v97, v97
	v_pk_mul_f32 v[94:95], v[82:83], v[94:95]
	v_pk_mul_f32 v[82:83], v[84:85], v[104:105] op_sel_hi:[1,0]
	v_add_f32_e32 v96, 1.0, v96
	v_pk_mul_f32 v[82:83], v[90:91], v[82:83]
	v_add_f32_e32 v97, 1.0, v97
	v_pk_mul_f32 v[90:91], v[82:83], v[92:93]
	v_fmamk_f32 v82, v138, 0x3a800000, v221
	v_rsq_f32_e32 v92, v82
	v_rcp_f32_e32 v96, v96
	v_rcp_f32_e32 v97, v97
	v_add_u32_e32 v93, s53, v105
	v_pk_mul_f32 v[78:79], v[78:79], v[92:93] op_sel_hi:[1,0]
	v_cvt_pk_bf16_f32 v82, v86, v87
	v_pk_mul_f32 v[88:89], v[88:89], v[96:97]
	v_mul_f32_e32 v84, 0xbfb8aa3b, v78
	v_lshlrev_b32_e32 v96, 1, v93
	v_cvt_pk_bf16_f32 v83, v88, v89
	v_exp_f32_e32 v86, v84
	v_cvt_pk_bf16_f32 v84, v94, v95
	v_cvt_pk_bf16_f32 v85, v90, v91
	buffer_store_dwordx4 v[82:85], v96, s[20:23], 0 offen sc1
	v_pk_mul_f32 v[70:71], v[70:71], v[92:93] op_sel_hi:[1,0]
	v_pk_mul_f32 v[74:75], v[74:75], v[92:93] op_sel_hi:[1,0]
	v_mul_f32_e32 v83, 0xbfb8aa3b, v79
	v_exp_f32_e32 v83, v83
	v_add_f32_e32 v82, 1.0, v86
	v_pk_mul_f32 v[70:71], v[78:79], v[70:71]
	v_rcp_f32_e32 v82, v82
	v_add_f32_e32 v78, 1.0, v83
	v_rcp_f32_e32 v83, v78
	v_pk_mul_f32 v[78:79], v[80:81], v[92:93] op_sel_hi:[1,0]
	v_pk_mul_f32 v[72:73], v[72:73], v[92:93] op_sel_hi:[1,0]
	v_mul_f32_e32 v81, 0xbfb8aa3b, v79
	v_pk_mul_f32 v[70:71], v[70:71], v[82:83]
	v_mul_f32_e32 v82, 0xbfb8aa3b, v74
	v_pk_mul_f32 v[72:73], v[78:79], v[72:73]
	v_mul_f32_e32 v79, 0xbfb8aa3b, v75
	v_pk_mul_f32 v[66:67], v[66:67], v[92:93] op_sel_hi:[1,0]
	v_exp_f32_e32 v82, v82
	v_exp_f32_e32 v79, v79
	v_pk_mul_f32 v[66:67], v[74:75], v[66:67]
	v_pk_mul_f32 v[74:75], v[76:77], v[92:93] op_sel_hi:[1,0]
	v_mul_f32_e32 v80, 0xbfb8aa3b, v78
	v_mul_f32_e32 v76, 0xbfb8aa3b, v74
	v_mul_f32_e32 v77, 0xbfb8aa3b, v75
	v_exp_f32_e32 v76, v76
	v_exp_f32_e32 v77, v77
	v_add_f32_e32 v78, 1.0, v82
	v_add_f32_e32 v79, 1.0, v79
	v_rcp_f32_e32 v78, v78
	v_rcp_f32_e32 v79, v79
	v_add_f32_e32 v76, 1.0, v76
	v_add_f32_e32 v77, 1.0, v77
	v_rcp_f32_e32 v76, v76
	v_rcp_f32_e32 v77, v77
	v_exp_f32_e32 v80, v80
	v_exp_f32_e32 v81, v81
	v_pk_mul_f32 v[78:79], v[66:67], v[78:79]
	v_pk_mul_f32 v[66:67], v[68:69], v[92:93] op_sel_hi:[1,0]
	v_add_f32_e32 v80, 1.0, v80
	v_pk_mul_f32 v[66:67], v[74:75], v[66:67]
	v_add_f32_e32 v81, 1.0, v81
	v_pk_mul_f32 v[74:75], v[66:67], v[76:77]
	v_fmamk_f32 v66, v139, 0x3a800000, v221
	v_rsq_f32_e32 v76, v66
	v_rcp_f32_e32 v80, v80
	v_rcp_f32_e32 v81, v81
	v_add_u32_e32 v77, s53, v93
	v_pk_mul_f32 v[62:63], v[62:63], v[76:77] op_sel_hi:[1,0]
	v_cvt_pk_bf16_f32 v66, v70, v71
	v_pk_mul_f32 v[72:73], v[72:73], v[80:81]
	v_mul_f32_e32 v68, 0xbfb8aa3b, v62
	v_lshlrev_b32_e32 v80, 1, v77
	v_cvt_pk_bf16_f32 v67, v72, v73
	v_exp_f32_e32 v70, v68
	v_cvt_pk_bf16_f32 v68, v78, v79
	v_cvt_pk_bf16_f32 v69, v74, v75
	buffer_store_dwordx4 v[66:69], v80, s[20:23], 0 offen sc1
	v_pk_mul_f32 v[54:55], v[54:55], v[76:77] op_sel_hi:[1,0]
	v_pk_mul_f32 v[58:59], v[58:59], v[76:77] op_sel_hi:[1,0]
	v_mul_f32_e32 v67, 0xbfb8aa3b, v63
	v_exp_f32_e32 v67, v67
	v_add_f32_e32 v66, 1.0, v70
	v_pk_mul_f32 v[54:55], v[62:63], v[54:55]
	v_rcp_f32_e32 v66, v66
	v_add_f32_e32 v62, 1.0, v67
	v_rcp_f32_e32 v67, v62
	v_pk_mul_f32 v[62:63], v[64:65], v[76:77] op_sel_hi:[1,0]
	v_pk_mul_f32 v[56:57], v[56:57], v[76:77] op_sel_hi:[1,0]
	v_mul_f32_e32 v65, 0xbfb8aa3b, v63
	v_pk_mul_f32 v[54:55], v[54:55], v[66:67]
	v_mul_f32_e32 v66, 0xbfb8aa3b, v58
	v_pk_mul_f32 v[56:57], v[62:63], v[56:57]
	v_mul_f32_e32 v63, 0xbfb8aa3b, v59
	v_pk_mul_f32 v[50:51], v[50:51], v[76:77] op_sel_hi:[1,0]
	v_exp_f32_e32 v66, v66
	v_exp_f32_e32 v63, v63
	v_pk_mul_f32 v[50:51], v[58:59], v[50:51]
	v_pk_mul_f32 v[58:59], v[60:61], v[76:77] op_sel_hi:[1,0]
	v_mul_f32_e32 v64, 0xbfb8aa3b, v62
	v_mul_f32_e32 v60, 0xbfb8aa3b, v58
	v_mul_f32_e32 v61, 0xbfb8aa3b, v59
	v_exp_f32_e32 v60, v60
	v_exp_f32_e32 v61, v61
	v_add_f32_e32 v62, 1.0, v66
	v_add_f32_e32 v63, 1.0, v63
	v_rcp_f32_e32 v62, v62
	v_rcp_f32_e32 v63, v63
	v_add_f32_e32 v60, 1.0, v60
	v_add_f32_e32 v61, 1.0, v61
	v_rcp_f32_e32 v60, v60
	v_rcp_f32_e32 v61, v61
	v_exp_f32_e32 v64, v64
	v_exp_f32_e32 v65, v65
	v_pk_mul_f32 v[62:63], v[50:51], v[62:63]
	v_pk_mul_f32 v[50:51], v[52:53], v[76:77] op_sel_hi:[1,0]
	v_add_f32_e32 v64, 1.0, v64
	v_pk_mul_f32 v[50:51], v[58:59], v[50:51]
	v_add_f32_e32 v65, 1.0, v65
	v_pk_mul_f32 v[58:59], v[50:51], v[60:61]
	v_fmamk_f32 v50, v140, 0x3a800000, v221
	v_rsq_f32_e32 v60, v50
	v_rcp_f32_e32 v64, v64
	v_rcp_f32_e32 v65, v65
	v_add_u32_e32 v61, s0, v77
	v_pk_mul_f32 v[46:47], v[46:47], v[60:61] op_sel_hi:[1,0]
	v_cvt_pk_bf16_f32 v50, v54, v55
	v_pk_mul_f32 v[56:57], v[56:57], v[64:65]
	v_mul_f32_e32 v52, 0xbfb8aa3b, v46
	v_lshlrev_b32_e32 v64, 1, v61
	v_cvt_pk_bf16_f32 v51, v56, v57
	v_exp_f32_e32 v54, v52
	v_cvt_pk_bf16_f32 v52, v62, v63
	v_cvt_pk_bf16_f32 v53, v58, v59
	buffer_store_dwordx4 v[50:53], v64, s[20:23], 0 offen sc1
	v_pk_mul_f32 v[38:39], v[38:39], v[60:61] op_sel_hi:[1,0]
	v_pk_mul_f32 v[42:43], v[42:43], v[60:61] op_sel_hi:[1,0]
	v_mul_f32_e32 v51, 0xbfb8aa3b, v47
	v_exp_f32_e32 v51, v51
	v_add_f32_e32 v50, 1.0, v54
	v_pk_mul_f32 v[38:39], v[46:47], v[38:39]
	v_rcp_f32_e32 v50, v50
	v_add_f32_e32 v46, 1.0, v51
	v_rcp_f32_e32 v51, v46
	v_pk_mul_f32 v[46:47], v[48:49], v[60:61] op_sel_hi:[1,0]
	v_pk_mul_f32 v[40:41], v[40:41], v[60:61] op_sel_hi:[1,0]
	v_mul_f32_e32 v49, 0xbfb8aa3b, v47
	v_pk_mul_f32 v[38:39], v[38:39], v[50:51]
	v_mul_f32_e32 v50, 0xbfb8aa3b, v42
	v_pk_mul_f32 v[40:41], v[46:47], v[40:41]
	v_mul_f32_e32 v47, 0xbfb8aa3b, v43
	v_pk_mul_f32 v[34:35], v[34:35], v[60:61] op_sel_hi:[1,0]
	v_exp_f32_e32 v50, v50
	v_exp_f32_e32 v47, v47
	v_pk_mul_f32 v[34:35], v[42:43], v[34:35]
	v_pk_mul_f32 v[42:43], v[44:45], v[60:61] op_sel_hi:[1,0]
	v_mul_f32_e32 v48, 0xbfb8aa3b, v46
	v_mul_f32_e32 v44, 0xbfb8aa3b, v42
	v_mul_f32_e32 v45, 0xbfb8aa3b, v43
	v_exp_f32_e32 v44, v44
	v_exp_f32_e32 v45, v45
	v_add_f32_e32 v46, 1.0, v50
	v_add_f32_e32 v47, 1.0, v47
	v_rcp_f32_e32 v46, v46
	v_rcp_f32_e32 v47, v47
	v_add_f32_e32 v44, 1.0, v44
	v_add_f32_e32 v45, 1.0, v45
	v_rcp_f32_e32 v44, v44
	v_rcp_f32_e32 v45, v45
	v_exp_f32_e32 v48, v48
	v_exp_f32_e32 v49, v49
	v_pk_mul_f32 v[46:47], v[34:35], v[46:47]
	v_pk_mul_f32 v[34:35], v[36:37], v[60:61] op_sel_hi:[1,0]
	v_add_f32_e32 v48, 1.0, v48
	v_pk_mul_f32 v[34:35], v[42:43], v[34:35]
	v_add_f32_e32 v49, 1.0, v49
	v_pk_mul_f32 v[42:43], v[34:35], v[44:45]
	v_fmamk_f32 v34, v131, 0x3a800000, v221
	v_rsq_f32_e32 v44, v34
	v_rcp_f32_e32 v48, v48
	v_rcp_f32_e32 v49, v49
	v_add_u32_e32 v45, s53, v61
	v_pk_mul_f32 v[30:31], v[30:31], v[44:45] op_sel_hi:[1,0]
	v_cvt_pk_bf16_f32 v34, v38, v39
	v_pk_mul_f32 v[40:41], v[40:41], v[48:49]
	v_mul_f32_e32 v36, 0xbfb8aa3b, v30
	v_lshlrev_b32_e32 v48, 1, v45
	v_cvt_pk_bf16_f32 v35, v40, v41
	v_exp_f32_e32 v38, v36
	v_cvt_pk_bf16_f32 v36, v46, v47
	v_cvt_pk_bf16_f32 v37, v42, v43
	buffer_store_dwordx4 v[34:37], v48, s[20:23], 0 offen sc1
	v_pk_mul_f32 v[22:23], v[22:23], v[44:45] op_sel_hi:[1,0]
	v_pk_mul_f32 v[26:27], v[26:27], v[44:45] op_sel_hi:[1,0]
	v_mul_f32_e32 v35, 0xbfb8aa3b, v31
	v_exp_f32_e32 v35, v35
	v_add_f32_e32 v34, 1.0, v38
	v_pk_mul_f32 v[22:23], v[30:31], v[22:23]
	v_rcp_f32_e32 v34, v34
	v_add_f32_e32 v30, 1.0, v35
	v_rcp_f32_e32 v35, v30
	v_pk_mul_f32 v[30:31], v[32:33], v[44:45] op_sel_hi:[1,0]
	v_pk_mul_f32 v[24:25], v[24:25], v[44:45] op_sel_hi:[1,0]
	v_mul_f32_e32 v33, 0xbfb8aa3b, v31
	v_pk_mul_f32 v[22:23], v[22:23], v[34:35]
	v_mul_f32_e32 v34, 0xbfb8aa3b, v26
	v_pk_mul_f32 v[24:25], v[30:31], v[24:25]
	v_mul_f32_e32 v31, 0xbfb8aa3b, v27
	v_pk_mul_f32 v[18:19], v[18:19], v[44:45] op_sel_hi:[1,0]
	v_exp_f32_e32 v34, v34
	v_exp_f32_e32 v31, v31
	v_pk_mul_f32 v[18:19], v[26:27], v[18:19]
	v_pk_mul_f32 v[26:27], v[28:29], v[44:45] op_sel_hi:[1,0]
	v_mul_f32_e32 v32, 0xbfb8aa3b, v30
	v_mul_f32_e32 v28, 0xbfb8aa3b, v26
	v_mul_f32_e32 v29, 0xbfb8aa3b, v27
	v_exp_f32_e32 v28, v28
	v_exp_f32_e32 v29, v29
	v_add_f32_e32 v30, 1.0, v34
	v_add_f32_e32 v31, 1.0, v31
	v_rcp_f32_e32 v30, v30
	v_rcp_f32_e32 v31, v31
	v_add_f32_e32 v28, 1.0, v28
	v_add_f32_e32 v29, 1.0, v29
	v_rcp_f32_e32 v28, v28
	v_rcp_f32_e32 v29, v29
	v_exp_f32_e32 v32, v32
	v_exp_f32_e32 v33, v33
	v_pk_mul_f32 v[30:31], v[18:19], v[30:31]
	v_pk_mul_f32 v[18:19], v[20:21], v[44:45] op_sel_hi:[1,0]
	v_add_f32_e32 v32, 1.0, v32
	v_pk_mul_f32 v[18:19], v[26:27], v[18:19]
	v_add_f32_e32 v33, 1.0, v33
	v_pk_mul_f32 v[26:27], v[18:19], v[28:29]
	v_fmamk_f32 v18, v130, 0x3a800000, v221
	v_rsq_f32_e32 v28, v18
	v_rcp_f32_e32 v32, v32
	v_rcp_f32_e32 v33, v33
	v_add_u32_e32 v29, s53, v45
	v_pk_mul_f32 v[14:15], v[14:15], v[28:29] op_sel_hi:[1,0]
	v_cvt_pk_bf16_f32 v18, v22, v23
	v_pk_mul_f32 v[24:25], v[24:25], v[32:33]
	v_mul_f32_e32 v20, 0xbfb8aa3b, v14
	v_lshlrev_b32_e32 v32, 1, v29
	v_cvt_pk_bf16_f32 v19, v24, v25
	v_exp_f32_e32 v22, v20
	v_cvt_pk_bf16_f32 v20, v30, v31
	v_cvt_pk_bf16_f32 v21, v26, v27
	buffer_store_dwordx4 v[18:21], v32, s[20:23], 0 offen sc1
	v_pk_mul_f32 v[6:7], v[6:7], v[28:29] op_sel_hi:[1,0]
	v_pk_mul_f32 v[10:11], v[10:11], v[28:29] op_sel_hi:[1,0]
	v_mul_f32_e32 v19, 0xbfb8aa3b, v15
	v_exp_f32_e32 v19, v19
	v_add_f32_e32 v18, 1.0, v22
	v_pk_mul_f32 v[6:7], v[14:15], v[6:7]
	v_rcp_f32_e32 v18, v18
	v_add_f32_e32 v14, 1.0, v19
	v_rcp_f32_e32 v19, v14
	v_pk_mul_f32 v[14:15], v[16:17], v[28:29] op_sel_hi:[1,0]
	v_pk_mul_f32 v[8:9], v[8:9], v[28:29] op_sel_hi:[1,0]
	v_mul_f32_e32 v17, 0xbfb8aa3b, v15
	v_pk_mul_f32 v[6:7], v[6:7], v[18:19]
	v_mul_f32_e32 v18, 0xbfb8aa3b, v10
	v_pk_mul_f32 v[8:9], v[14:15], v[8:9]
	v_mul_f32_e32 v15, 0xbfb8aa3b, v11
	v_pk_mul_f32 v[2:3], v[2:3], v[28:29] op_sel_hi:[1,0]
	v_exp_f32_e32 v18, v18
	v_exp_f32_e32 v15, v15
	v_pk_mul_f32 v[2:3], v[10:11], v[2:3]
	v_pk_mul_f32 v[10:11], v[12:13], v[28:29] op_sel_hi:[1,0]
	v_mul_f32_e32 v16, 0xbfb8aa3b, v14
	v_mul_f32_e32 v12, 0xbfb8aa3b, v10
	v_mul_f32_e32 v13, 0xbfb8aa3b, v11
	v_exp_f32_e32 v16, v16
	v_exp_f32_e32 v17, v17
	v_exp_f32_e32 v12, v12
	v_exp_f32_e32 v13, v13
	v_add_f32_e32 v14, 1.0, v18
	v_add_f32_e32 v15, 1.0, v15
	v_rcp_f32_e32 v14, v14
	v_rcp_f32_e32 v15, v15
	v_add_f32_e32 v16, 1.0, v16
	v_add_f32_e32 v17, 1.0, v17
	v_add_f32_e32 v12, 1.0, v12
	v_add_f32_e32 v13, 1.0, v13
	v_rcp_f32_e32 v16, v16
	v_rcp_f32_e32 v17, v17
	v_rcp_f32_e32 v12, v12
	v_rcp_f32_e32 v13, v13
	v_pk_mul_f32 v[14:15], v[2:3], v[14:15]
	v_pk_mul_f32 v[2:3], v[4:5], v[28:29] op_sel_hi:[1,0]
	v_pk_mul_f32 v[8:9], v[8:9], v[16:17]
	v_pk_mul_f32 v[2:3], v[10:11], v[2:3]
	v_cvt_pk_bf16_f32 v4, v14, v15
	v_pk_mul_f32 v[10:11], v[2:3], v[12:13]
	v_add_lshl_u32 v12, v29, s53, 1
	v_cvt_pk_bf16_f32 v2, v6, v7
	v_cvt_pk_bf16_f32 v3, v8, v9
	v_cvt_pk_bf16_f32 v5, v10, v11
	buffer_store_dwordx4 v[2:5], v12, s[20:23], 0 offen sc1
	s_and_b64 vcc, exec, s[40:41]
	s_mov_b64 s[34:35], -1
	s_cbranch_vccnz .LBB0_161
	s_branch .LBB0_225
